# P7 epilogue: drop per-row-group vmcnt(0) that only serialised on previous group's stores
# speedup vs baseline: 1.0006x; 1.0006x over previous
.LBB0_931:
	v_cmp_eq_u32_e32 vcc, 0, v130
	s_cbranch_vccnz .LBB0_942
	v_lshl_add_u32 v202, s43, 8, v1
	v_lshl_or_b32 v200, s42, 8, v221
	v_add_u32_e32 v216, 16, v202
	v_ashrrev_i32_e32 v201, 31, v200
	v_ashrrev_i32_e32 v217, 31, v216
	v_lshl_add_u64 v[218:219], v[200:201], 1, s[96:97]
	v_lshlrev_b64 v[130:131], 11, v[216:217]
	v_add_u32_e32 v214, 32, v202
	v_lshl_add_u64 v[130:131], v[218:219], 0, v[130:131]
	v_ashrrev_i32_e32 v215, 31, v214
	global_load_dwordx4 v[182:185], v[130:131], off nt
	global_load_dwordx4 v[178:181], v[130:131], off offset:256 nt
	v_lshlrev_b64 v[130:131], 11, v[214:215]
	v_add_u32_e32 v212, 48, v202
	v_lshl_add_u64 v[130:131], v[218:219], 0, v[130:131]
	v_ashrrev_i32_e32 v213, 31, v212
	global_load_dwordx4 v[174:177], v[130:131], off nt
	global_load_dwordx4 v[170:173], v[130:131], off offset:256 nt
	v_lshlrev_b64 v[130:131], 11, v[212:213]
	v_add_u32_e32 v210, 0x80, v202
	v_lshl_add_u64 v[130:131], v[218:219], 0, v[130:131]
	v_ashrrev_i32_e32 v211, 31, v210
	global_load_dwordx4 v[166:169], v[130:131], off nt
	global_load_dwordx4 v[162:165], v[130:131], off offset:256 nt
	v_lshlrev_b64 v[130:131], 11, v[210:211]
	v_add_u32_e32 v208, 0x90, v202
	v_lshl_add_u64 v[130:131], v[218:219], 0, v[130:131]
	v_ashrrev_i32_e32 v209, 31, v208
	global_load_dwordx4 v[158:161], v[130:131], off nt
	global_load_dwordx4 v[154:157], v[130:131], off offset:256 nt
	v_lshlrev_b64 v[130:131], 11, v[208:209]
	v_add_u32_e32 v206, 0xa0, v202
	v_lshl_add_u64 v[130:131], v[218:219], 0, v[130:131]
	v_ashrrev_i32_e32 v207, 31, v206
	global_load_dwordx4 v[150:153], v[130:131], off nt
	global_load_dwordx4 v[146:149], v[130:131], off offset:256 nt
	v_lshlrev_b64 v[130:131], 11, v[206:207]
	v_add_u32_e32 v204, 0xb0, v202
	v_lshl_add_u64 v[130:131], v[218:219], 0, v[130:131]
	v_ashrrev_i32_e32 v205, 31, v204
	global_load_dwordx4 v[142:145], v[130:131], off nt
	global_load_dwordx4 v[138:141], v[130:131], off offset:256 nt
	v_lshlrev_b64 v[130:131], 11, v[204:205]
	v_lshl_add_u64 v[130:131], v[218:219], 0, v[130:131]
	global_load_dwordx4 v[134:137], v[130:131], off nt
	s_nop 0
	global_load_dwordx4 v[130:133], v[130:131], off offset:256 nt
	v_cmp_gt_i32_e32 vcc, s30, v202
	s_and_saveexec_b64 s[10:11], vcc
	s_cbranch_execnz .LBB0_945
	s_waitcnt vmcnt(0)
	s_or_b64 exec, exec, s[10:11]
	v_cmp_gt_i32_e32 vcc, s31, v202
	s_and_saveexec_b64 s[10:11], vcc
	s_cbranch_execnz .LBB0_946

.LBB0_940:
	v_lshlrev_b64 v[18:19], 12, v[204:205]
	v_lshl_add_u64 v[18:19], s[70:71], 0, v[18:19]
	s_nop 0
	v_lshlrev_b32_e32 v20, 16, v134
	v_and_b32_e32 v21, 0xffff0000, v134
	v_lshlrev_b32_e32 v22, 16, v135
	v_and_b32_e32 v23, 0xffff0000, v135
	v_lshl_add_u64 v[18:19], v[200:201], 2, v[18:19]
	v_pk_add_f32 v[16:17], v[16:17], v[22:23]
	v_pk_add_f32 v[14:15], v[14:15], v[20:21]
	global_store_dwordx4 v[18:19], v[14:17], off
	s_nop 1
	v_lshlrev_b32_e32 v14, 16, v136
	v_and_b32_e32 v15, 0xffff0000, v136
	v_lshlrev_b32_e32 v16, 16, v137
	v_and_b32_e32 v17, 0xffff0000, v137
	v_pk_add_f32 v[12:13], v[12:13], v[16:17]
	v_pk_add_f32 v[10:11], v[10:11], v[14:15]
	global_store_dwordx4 v[18:19], v[10:13], off offset:16
	s_nop 1
	v_lshlrev_b32_e32 v10, 16, v130
	v_and_b32_e32 v11, 0xffff0000, v130
	v_lshlrev_b32_e32 v12, 16, v131
	v_and_b32_e32 v13, 0xffff0000, v131
	v_pk_add_f32 v[8:9], v[8:9], v[12:13]
	v_pk_add_f32 v[6:7], v[6:7], v[10:11]
	global_store_dwordx4 v[18:19], v[6:9], off offset:512
	s_nop 1
	v_lshlrev_b32_e32 v6, 16, v132
	v_and_b32_e32 v7, 0xffff0000, v132
	v_lshlrev_b32_e32 v8, 16, v133
	v_and_b32_e32 v9, 0xffff0000, v133
	v_pk_add_f32 v[4:5], v[4:5], v[8:9]
	v_pk_add_f32 v[2:3], v[2:3], v[6:7]
	global_store_dwordx4 v[18:19], v[2:5], off offset:528

.LBB0_946:
	v_lshlrev_b64 v[114:115], 12, v[216:217]
	v_lshl_add_u64 v[114:115], s[70:71], 0, v[114:115]
	s_nop 0
	v_lshlrev_b32_e32 v116, 16, v182
	v_and_b32_e32 v117, 0xffff0000, v182
	v_lshlrev_b32_e32 v118, 16, v183
	v_and_b32_e32 v119, 0xffff0000, v183
	v_lshl_add_u64 v[114:115], v[200:201], 2, v[114:115]
	v_pk_add_f32 v[112:113], v[112:113], v[118:119]
	v_pk_add_f32 v[110:111], v[110:111], v[116:117]
	global_store_dwordx4 v[114:115], v[110:113], off
	s_nop 1
	v_lshlrev_b32_e32 v110, 16, v184
	v_and_b32_e32 v111, 0xffff0000, v184
	v_lshlrev_b32_e32 v112, 16, v185
	v_and_b32_e32 v113, 0xffff0000, v185
	v_pk_add_f32 v[108:109], v[108:109], v[112:113]
	v_pk_add_f32 v[106:107], v[106:107], v[110:111]
	global_store_dwordx4 v[114:115], v[106:109], off offset:16
	s_nop 1
	v_lshlrev_b32_e32 v106, 16, v178
	v_and_b32_e32 v107, 0xffff0000, v178
	v_lshlrev_b32_e32 v108, 16, v179
	v_and_b32_e32 v109, 0xffff0000, v179
	v_pk_add_f32 v[104:105], v[104:105], v[108:109]
	v_pk_add_f32 v[102:103], v[102:103], v[106:107]
	global_store_dwordx4 v[114:115], v[102:105], off offset:512
	s_nop 1
	v_lshlrev_b32_e32 v102, 16, v180
	v_and_b32_e32 v103, 0xffff0000, v180
	v_lshlrev_b32_e32 v104, 16, v181
	v_and_b32_e32 v105, 0xffff0000, v181
	v_pk_add_f32 v[100:101], v[100:101], v[104:105]
	v_pk_add_f32 v[98:99], v[98:99], v[102:103]
	global_store_dwordx4 v[114:115], v[98:101], off offset:528
	s_or_b64 exec, exec, s[10:11]
	v_cmp_gt_i32_e32 vcc, s34, v202
	s_and_saveexec_b64 s[10:11], vcc
	s_cbranch_execz .LBB0_935
.LBB0_947:
	v_lshlrev_b64 v[98:99], 12, v[214:215]
	v_lshl_add_u64 v[98:99], s[70:71], 0, v[98:99]
	s_nop 0
	v_lshlrev_b32_e32 v100, 16, v174
	v_and_b32_e32 v101, 0xffff0000, v174
	v_lshlrev_b32_e32 v102, 16, v175
	v_and_b32_e32 v103, 0xffff0000, v175
	v_lshl_add_u64 v[98:99], v[200:201], 2, v[98:99]
	v_pk_add_f32 v[96:97], v[96:97], v[102:103]
	v_pk_add_f32 v[94:95], v[94:95], v[100:101]
	global_store_dwordx4 v[98:99], v[94:97], off
	s_nop 1
	v_lshlrev_b32_e32 v94, 16, v176
	v_and_b32_e32 v95, 0xffff0000, v176
	v_lshlrev_b32_e32 v96, 16, v177
	v_and_b32_e32 v97, 0xffff0000, v177
	v_pk_add_f32 v[92:93], v[92:93], v[96:97]
	v_pk_add_f32 v[90:91], v[90:91], v[94:95]
	global_store_dwordx4 v[98:99], v[90:93], off offset:16
	s_nop 1
	v_lshlrev_b32_e32 v90, 16, v170
	v_and_b32_e32 v91, 0xffff0000, v170
	v_lshlrev_b32_e32 v92, 16, v171
	v_and_b32_e32 v93, 0xffff0000, v171
	v_pk_add_f32 v[88:89], v[88:89], v[92:93]
	v_pk_add_f32 v[86:87], v[86:87], v[90:91]
	global_store_dwordx4 v[98:99], v[86:89], off offset:512
	s_nop 1
	v_lshlrev_b32_e32 v86, 16, v172
	v_and_b32_e32 v87, 0xffff0000, v172
	v_lshlrev_b32_e32 v88, 16, v173
	v_and_b32_e32 v89, 0xffff0000, v173
	v_pk_add_f32 v[84:85], v[84:85], v[88:89]
	v_pk_add_f32 v[82:83], v[82:83], v[86:87]
	global_store_dwordx4 v[98:99], v[82:85], off offset:528
	s_or_b64 exec, exec, s[10:11]
	v_cmp_gt_i32_e32 vcc, s35, v202
	s_and_saveexec_b64 s[10:11], vcc
	s_cbranch_execz .LBB0_936
.LBB0_948:
	v_lshlrev_b64 v[82:83], 12, v[212:213]
	v_lshl_add_u64 v[82:83], s[70:71], 0, v[82:83]
	s_nop 0
	v_lshlrev_b32_e32 v84, 16, v166
	v_and_b32_e32 v85, 0xffff0000, v166
	v_lshlrev_b32_e32 v86, 16, v167
	v_and_b32_e32 v87, 0xffff0000, v167
	v_lshl_add_u64 v[82:83], v[200:201], 2, v[82:83]
	v_pk_add_f32 v[80:81], v[80:81], v[86:87]
	v_pk_add_f32 v[78:79], v[78:79], v[84:85]
	global_store_dwordx4 v[82:83], v[78:81], off
	s_nop 1
	v_lshlrev_b32_e32 v78, 16, v168
	v_and_b32_e32 v79, 0xffff0000, v168
	v_lshlrev_b32_e32 v80, 16, v169
	v_and_b32_e32 v81, 0xffff0000, v169
	v_pk_add_f32 v[76:77], v[76:77], v[80:81]
	v_pk_add_f32 v[74:75], v[74:75], v[78:79]
	global_store_dwordx4 v[82:83], v[74:77], off offset:16
	s_nop 1
	v_lshlrev_b32_e32 v74, 16, v162
	v_and_b32_e32 v75, 0xffff0000, v162
	v_lshlrev_b32_e32 v76, 16, v163
	v_and_b32_e32 v77, 0xffff0000, v163
	v_pk_add_f32 v[72:73], v[72:73], v[76:77]
	v_pk_add_f32 v[70:71], v[70:71], v[74:75]
	global_store_dwordx4 v[82:83], v[70:73], off offset:512
	s_nop 1
	v_lshlrev_b32_e32 v70, 16, v164
	v_and_b32_e32 v71, 0xffff0000, v164
	v_lshlrev_b32_e32 v72, 16, v165
	v_and_b32_e32 v73, 0xffff0000, v165
	v_pk_add_f32 v[68:69], v[68:69], v[72:73]
	v_pk_add_f32 v[66:67], v[66:67], v[70:71]
	global_store_dwordx4 v[82:83], v[66:69], off offset:528
	s_or_b64 exec, exec, s[10:11]
	v_cmp_gt_i32_e32 vcc, s22, v202
	s_and_saveexec_b64 s[10:11], vcc
	s_cbranch_execz .LBB0_937
.LBB0_949:
	v_lshlrev_b64 v[66:67], 12, v[210:211]
	v_lshl_add_u64 v[66:67], s[70:71], 0, v[66:67]
	s_nop 0
	v_lshlrev_b32_e32 v68, 16, v158
	v_and_b32_e32 v69, 0xffff0000, v158
	v_lshlrev_b32_e32 v70, 16, v159
	v_and_b32_e32 v71, 0xffff0000, v159
	v_lshl_add_u64 v[66:67], v[200:201], 2, v[66:67]
	v_pk_add_f32 v[64:65], v[64:65], v[70:71]
	v_pk_add_f32 v[62:63], v[62:63], v[68:69]
	global_store_dwordx4 v[66:67], v[62:65], off
	s_nop 1
	v_lshlrev_b32_e32 v62, 16, v160
	v_and_b32_e32 v63, 0xffff0000, v160
	v_lshlrev_b32_e32 v64, 16, v161
	v_and_b32_e32 v65, 0xffff0000, v161
	v_pk_add_f32 v[60:61], v[60:61], v[64:65]
	v_pk_add_f32 v[58:59], v[58:59], v[62:63]
	global_store_dwordx4 v[66:67], v[58:61], off offset:16
	s_nop 1
	v_lshlrev_b32_e32 v58, 16, v154
	v_and_b32_e32 v59, 0xffff0000, v154
	v_lshlrev_b32_e32 v60, 16, v155
	v_and_b32_e32 v61, 0xffff0000, v155
	v_pk_add_f32 v[56:57], v[56:57], v[60:61]
	v_pk_add_f32 v[54:55], v[54:55], v[58:59]
	global_store_dwordx4 v[66:67], v[54:57], off offset:512
	s_nop 1
	v_lshlrev_b32_e32 v54, 16, v156
	v_and_b32_e32 v55, 0xffff0000, v156
	v_lshlrev_b32_e32 v56, 16, v157
	v_and_b32_e32 v57, 0xffff0000, v157
	v_pk_add_f32 v[52:53], v[52:53], v[56:57]
	v_pk_add_f32 v[50:51], v[50:51], v[54:55]
	global_store_dwordx4 v[66:67], v[50:53], off offset:528
	s_or_b64 exec, exec, s[10:11]
	v_cmp_gt_i32_e32 vcc, s36, v202
	s_and_saveexec_b64 s[10:11], vcc
	s_cbranch_execz .LBB0_938
.LBB0_950:
	v_lshlrev_b64 v[50:51], 12, v[208:209]
	v_lshl_add_u64 v[50:51], s[70:71], 0, v[50:51]
	s_nop 0
	v_lshlrev_b32_e32 v52, 16, v150
	v_and_b32_e32 v53, 0xffff0000, v150
	v_lshlrev_b32_e32 v54, 16, v151
	v_and_b32_e32 v55, 0xffff0000, v151
	v_lshl_add_u64 v[50:51], v[200:201], 2, v[50:51]
	v_pk_add_f32 v[48:49], v[48:49], v[54:55]
	v_pk_add_f32 v[46:47], v[46:47], v[52:53]
	global_store_dwordx4 v[50:51], v[46:49], off
	s_nop 1
	v_lshlrev_b32_e32 v46, 16, v152
	v_and_b32_e32 v47, 0xffff0000, v152
	v_lshlrev_b32_e32 v48, 16, v153
	v_and_b32_e32 v49, 0xffff0000, v153
	v_pk_add_f32 v[44:45], v[44:45], v[48:49]
	v_pk_add_f32 v[42:43], v[42:43], v[46:47]
	global_store_dwordx4 v[50:51], v[42:45], off offset:16
	s_nop 1
	v_lshlrev_b32_e32 v42, 16, v146
	v_and_b32_e32 v43, 0xffff0000, v146
	v_lshlrev_b32_e32 v44, 16, v147
	v_and_b32_e32 v45, 0xffff0000, v147
	v_pk_add_f32 v[40:41], v[40:41], v[44:45]
	v_pk_add_f32 v[38:39], v[38:39], v[42:43]
	global_store_dwordx4 v[50:51], v[38:41], off offset:512
	s_nop 1
	v_lshlrev_b32_e32 v38, 16, v148
	v_and_b32_e32 v39, 0xffff0000, v148
	v_lshlrev_b32_e32 v40, 16, v149
	v_and_b32_e32 v41, 0xffff0000, v149
	v_pk_add_f32 v[36:37], v[36:37], v[40:41]
	v_pk_add_f32 v[34:35], v[34:35], v[38:39]
	global_store_dwordx4 v[50:51], v[34:37], off offset:528
	s_or_b64 exec, exec, s[10:11]
	v_cmp_gt_i32_e32 vcc, s37, v202
	s_and_saveexec_b64 s[10:11], vcc
	s_cbranch_execz .LBB0_939
.LBB0_951:
	v_lshlrev_b64 v[34:35], 12, v[206:207]
	v_lshl_add_u64 v[34:35], s[70:71], 0, v[34:35]
	s_nop 0
	v_lshlrev_b32_e32 v36, 16, v142
	v_and_b32_e32 v37, 0xffff0000, v142
	v_lshlrev_b32_e32 v38, 16, v143
	v_and_b32_e32 v39, 0xffff0000, v143
	v_lshl_add_u64 v[34:35], v[200:201], 2, v[34:35]
	v_pk_add_f32 v[32:33], v[32:33], v[38:39]
	v_pk_add_f32 v[30:31], v[30:31], v[36:37]
	global_store_dwordx4 v[34:35], v[30:33], off
	s_nop 1
	v_lshlrev_b32_e32 v30, 16, v144
	v_and_b32_e32 v31, 0xffff0000, v144
	v_lshlrev_b32_e32 v32, 16, v145
	v_and_b32_e32 v33, 0xffff0000, v145
	v_pk_add_f32 v[28:29], v[28:29], v[32:33]
	v_pk_add_f32 v[26:27], v[26:27], v[30:31]
	global_store_dwordx4 v[34:35], v[26:29], off offset:16
	s_nop 1
	v_lshlrev_b32_e32 v26, 16, v138
	v_and_b32_e32 v27, 0xffff0000, v138
	v_lshlrev_b32_e32 v28, 16, v139
	v_and_b32_e32 v29, 0xffff0000, v139
	v_pk_add_f32 v[24:25], v[24:25], v[28:29]
	v_pk_add_f32 v[22:23], v[22:23], v[26:27]
	global_store_dwordx4 v[34:35], v[22:25], off offset:512
	s_nop 1
	v_lshlrev_b32_e32 v22, 16, v140
	v_and_b32_e32 v23, 0xffff0000, v140
	v_lshlrev_b32_e32 v24, 16, v141
	v_and_b32_e32 v25, 0xffff0000, v141
	v_pk_add_f32 v[20:21], v[20:21], v[24:25]
	v_pk_add_f32 v[18:19], v[18:19], v[22:23]
	global_store_dwordx4 v[34:35], v[18:21], off offset:528
	s_or_b64 exec, exec, s[10:11]
	v_cmp_gt_i32_e32 vcc, s38, v202
	s_and_saveexec_b64 s[10:11], vcc
	s_cbranch_execnz .LBB0_940
	s_branch .LBB0_941
